# prologue GEMV: silu(c) staging loads batched (36 in flight) instead of one serialized load per iteration
# speedup vs baseline: 1.0003x; 1.0003x over previous
; __device__ __forceinline__ float silu_f(float v) { return v * __builtin_amdgcn_rcpf(1.0f + __expf(-v)); }
;     __device__ __forceinline__ const char* b(const pg8::Unit& u) const { return (const char*)ws + boff + (size_t)u.pn * 256 * K_ * 2 + (u.kq < 0 ? 0 : u.kq * (K_ / 4) * 2); }
;     __device__ __forceinline__ const char* b(const pg8::Unit& u) const { return (const char*)ws + boff + (size_t)u.pn * 256 * D * 2; }
;     __device__ __forceinline__ const char* b(const pg8::Unit& u) const { return (const char*)ws + boff + (size_t)u.pn * 256 * D * 2; }
;     __device__ __forceinline__ const char* b(const pg8::Unit& u) const { return (const char*)ws + WS_A + ((size_t)u.pn * 256 * D + (size_t)(u.pm >> 1) * 256) * 2; }
; __device__ __forceinline__ void p0_prologue(Frame& F) {
;     ...
;         for (int it = gw; it < NIT; it += NGW) {
;             const int ks = it % NKS, cg = (it / NKS) % NCG, L = it / (NKS * NCG), k0 = ks * 256;
;             for (int e = lane; e < 9 * 256; e += 64) { const int k = e & 255, b = e >> 8; const float v = (b < 8) ? c[b * D + k0 + k] : cc[k0 + k]; scr[k * 12 + b] = silu_f(v); }
.LBB0_19:
	s_ashr_i32 s4, s38, 31
	s_lshr_b32 s4, s4, 29
	s_add_i32 s39, s38, s4
	s_and_b32 s4, s39, -8
	s_sub_i32 s4, s38, s4
	s_lshl_b32 s5, s4, 8
	s_and_saveexec_b64 s[16:17], s[0:1]
	s_cbranch_execz .LBB0_22
	v_lshlrev_b32_e32 v48, 2, v44
	v_mul_u32_u24_e32 v47, 48, v44
	s_lshl_b32 s26, s5, 2
	s_add_u32 s100, s14, s26
	s_addc_u32 s101, s15, 0
	s_add_u32 s26, s10, s26
	s_addc_u32 s27, s11, 0
	v_add_u32_e32 v47, s28, v47
	global_load_dword v50, v48, s[26:27]
	global_load_dword v51, v48, s[26:27] offset:256
	global_load_dword v52, v48, s[26:27] offset:512
	global_load_dword v53, v48, s[26:27] offset:768
	v_add_u32_e32 v49, 0x2000, v48
	global_load_dword v54, v49, s[26:27]
	global_load_dword v55, v49, s[26:27] offset:256
	global_load_dword v56, v49, s[26:27] offset:512
	global_load_dword v57, v49, s[26:27] offset:768
	v_add_u32_e32 v49, 0x4000, v48
	global_load_dword v58, v49, s[26:27]
	global_load_dword v59, v49, s[26:27] offset:256
	global_load_dword v60, v49, s[26:27] offset:512
	global_load_dword v61, v49, s[26:27] offset:768
	v_add_u32_e32 v49, 0x6000, v48
	global_load_dword v62, v49, s[26:27]
	global_load_dword v63, v49, s[26:27] offset:256
	global_load_dword v64, v49, s[26:27] offset:512
	global_load_dword v65, v49, s[26:27] offset:768
	v_add_u32_e32 v49, 0x8000, v48
	global_load_dword v66, v49, s[26:27]
	global_load_dword v67, v49, s[26:27] offset:256
	global_load_dword v68, v49, s[26:27] offset:512
	global_load_dword v69, v49, s[26:27] offset:768
	v_add_u32_e32 v49, 0xa000, v48
	global_load_dword v70, v49, s[26:27]
	global_load_dword v71, v49, s[26:27] offset:256
	global_load_dword v72, v49, s[26:27] offset:512
	global_load_dword v73, v49, s[26:27] offset:768
	v_add_u32_e32 v49, 0xc000, v48
	global_load_dword v74, v49, s[26:27]
	global_load_dword v75, v49, s[26:27] offset:256
	global_load_dword v76, v49, s[26:27] offset:512
	global_load_dword v77, v49, s[26:27] offset:768
	v_add_u32_e32 v49, 0xe000, v48
	global_load_dword v78, v49, s[26:27]
	global_load_dword v79, v49, s[26:27] offset:256
	global_load_dword v80, v49, s[26:27] offset:512
	global_load_dword v81, v49, s[26:27] offset:768
	global_load_dword v82, v48, s[100:101]
	global_load_dword v83, v48, s[100:101] offset:256
	global_load_dword v84, v48, s[100:101] offset:512
	global_load_dword v85, v48, s[100:101] offset:768
	s_waitcnt vmcnt(32)
	v_mul_f32_e32 v86, 0xbfb8aa3b, v50
	v_mul_f32_e32 v87, 0xbfb8aa3b, v51
	v_mul_f32_e32 v88, 0xbfb8aa3b, v52
	v_mul_f32_e32 v89, 0xbfb8aa3b, v53
	v_exp_f32_e32 v86, v86
	v_exp_f32_e32 v87, v87
	v_exp_f32_e32 v88, v88
	v_exp_f32_e32 v89, v89
	s_nop 0
	v_add_f32_e32 v86, 1.0, v86
	v_add_f32_e32 v87, 1.0, v87
	v_add_f32_e32 v88, 1.0, v88
	v_add_f32_e32 v89, 1.0, v89
	v_rcp_f32_e32 v86, v86
	v_rcp_f32_e32 v87, v87
	v_rcp_f32_e32 v88, v88
	v_rcp_f32_e32 v89, v89
	s_nop 0
	v_mul_f32_e32 v86, v50, v86
	v_mul_f32_e32 v87, v51, v87
	v_mul_f32_e32 v88, v52, v88
	v_mul_f32_e32 v89, v53, v89
	ds_write_b32 v47, v86 offset:0
	ds_write_b32 v47, v87 offset:3072
	ds_write_b32 v47, v88 offset:6144
	ds_write_b32 v47, v89 offset:9216
	s_waitcnt vmcnt(28)
	v_mul_f32_e32 v86, 0xbfb8aa3b, v54
	v_mul_f32_e32 v87, 0xbfb8aa3b, v55
	v_mul_f32_e32 v88, 0xbfb8aa3b, v56
	v_mul_f32_e32 v89, 0xbfb8aa3b, v57
	v_exp_f32_e32 v86, v86
	v_exp_f32_e32 v87, v87
	v_exp_f32_e32 v88, v88
	v_exp_f32_e32 v89, v89
	s_nop 0
	v_add_f32_e32 v86, 1.0, v86
	v_add_f32_e32 v87, 1.0, v87
	v_add_f32_e32 v88, 1.0, v88
	v_add_f32_e32 v89, 1.0, v89
	v_rcp_f32_e32 v86, v86
	v_rcp_f32_e32 v87, v87
	v_rcp_f32_e32 v88, v88
	v_rcp_f32_e32 v89, v89
	s_nop 0
	v_mul_f32_e32 v86, v54, v86
	v_mul_f32_e32 v87, v55, v87
	v_mul_f32_e32 v88, v56, v88
	v_mul_f32_e32 v89, v57, v89
	ds_write_b32 v47, v86 offset:4
	ds_write_b32 v47, v87 offset:3076
	ds_write_b32 v47, v88 offset:6148
	ds_write_b32 v47, v89 offset:9220
	s_waitcnt vmcnt(24)
	v_mul_f32_e32 v86, 0xbfb8aa3b, v58
	v_mul_f32_e32 v87, 0xbfb8aa3b, v59
	v_mul_f32_e32 v88, 0xbfb8aa3b, v60
	v_mul_f32_e32 v89, 0xbfb8aa3b, v61
	v_exp_f32_e32 v86, v86
	v_exp_f32_e32 v87, v87
	v_exp_f32_e32 v88, v88
	v_exp_f32_e32 v89, v89
	s_nop 0
	v_add_f32_e32 v86, 1.0, v86
	v_add_f32_e32 v87, 1.0, v87
	v_add_f32_e32 v88, 1.0, v88
	v_add_f32_e32 v89, 1.0, v89
	v_rcp_f32_e32 v86, v86
	v_rcp_f32_e32 v87, v87
	v_rcp_f32_e32 v88, v88
	v_rcp_f32_e32 v89, v89
	s_nop 0
	v_mul_f32_e32 v86, v58, v86
	v_mul_f32_e32 v87, v59, v87
	v_mul_f32_e32 v88, v60, v88
	v_mul_f32_e32 v89, v61, v89
	ds_write_b32 v47, v86 offset:8
	ds_write_b32 v47, v87 offset:3080
	ds_write_b32 v47, v88 offset:6152
	ds_write_b32 v47, v89 offset:9224
	s_waitcnt vmcnt(20)
; __device__ __forceinline__ float silu_f(float v) { return v * __builtin_amdgcn_rcpf(1.0f + __expf(-v)); }
;     __device__ __forceinline__ const char* b(const pg8::Unit& u) const { return (const char*)ws + boff + (size_t)u.pn * 256 * K_ * 2 + (u.kq < 0 ? 0 : u.kq * (K_ / 4) * 2); }
;     __device__ __forceinline__ const char* b(const pg8::Unit& u) const { return (const char*)ws + boff + (size_t)u.pn * 256 * D * 2; }
;     __device__ __forceinline__ const char* b(const pg8::Unit& u) const { return (const char*)ws + boff + (size_t)u.pn * 256 * D * 2; }
;     __device__ __forceinline__ const char* b(const pg8::Unit& u) const { return (const char*)ws + WS_A + ((size_t)u.pn * 256 * D + (size_t)(u.pm >> 1) * 256) * 2; }
; __device__ __forceinline__ void p0_prologue(Frame& F) {
;     ...
;             for (int e = lane; e < 9 * 256; e += 64) { const int k = e & 255, b = e >> 8; const float v = (b < 8) ? c[b * D + k0 + k] : cc[k0 + k]; scr[k * 12 + b] = silu_f(v); }
	v_mul_f32_e32 v86, 0xbfb8aa3b, v62
	v_mul_f32_e32 v87, 0xbfb8aa3b, v63
	v_mul_f32_e32 v88, 0xbfb8aa3b, v64
	v_mul_f32_e32 v89, 0xbfb8aa3b, v65
	v_exp_f32_e32 v86, v86
	v_exp_f32_e32 v87, v87
	v_exp_f32_e32 v88, v88
	v_exp_f32_e32 v89, v89
	s_nop 0
	v_add_f32_e32 v86, 1.0, v86
	v_add_f32_e32 v87, 1.0, v87
	v_add_f32_e32 v88, 1.0, v88
	v_add_f32_e32 v89, 1.0, v89
	v_rcp_f32_e32 v86, v86
	v_rcp_f32_e32 v87, v87
	v_rcp_f32_e32 v88, v88
	v_rcp_f32_e32 v89, v89
	s_nop 0
	v_mul_f32_e32 v86, v62, v86
	v_mul_f32_e32 v87, v63, v87
	v_mul_f32_e32 v88, v64, v88
	v_mul_f32_e32 v89, v65, v89
	ds_write_b32 v47, v86 offset:12
	ds_write_b32 v47, v87 offset:3084
	ds_write_b32 v47, v88 offset:6156
	ds_write_b32 v47, v89 offset:9228
	s_waitcnt vmcnt(16)
	v_mul_f32_e32 v86, 0xbfb8aa3b, v66
	v_mul_f32_e32 v87, 0xbfb8aa3b, v67
	v_mul_f32_e32 v88, 0xbfb8aa3b, v68
	v_mul_f32_e32 v89, 0xbfb8aa3b, v69
	v_exp_f32_e32 v86, v86
	v_exp_f32_e32 v87, v87
	v_exp_f32_e32 v88, v88
	v_exp_f32_e32 v89, v89
	s_nop 0
	v_add_f32_e32 v86, 1.0, v86
	v_add_f32_e32 v87, 1.0, v87
	v_add_f32_e32 v88, 1.0, v88
	v_add_f32_e32 v89, 1.0, v89
	v_rcp_f32_e32 v86, v86
	v_rcp_f32_e32 v87, v87
	v_rcp_f32_e32 v88, v88
	v_rcp_f32_e32 v89, v89
	s_nop 0
	v_mul_f32_e32 v86, v66, v86
	v_mul_f32_e32 v87, v67, v87
	v_mul_f32_e32 v88, v68, v88
	v_mul_f32_e32 v89, v69, v89
	ds_write_b32 v47, v86 offset:16
	ds_write_b32 v47, v87 offset:3088
	ds_write_b32 v47, v88 offset:6160
	ds_write_b32 v47, v89 offset:9232
	s_waitcnt vmcnt(12)
	v_mul_f32_e32 v86, 0xbfb8aa3b, v70
	v_mul_f32_e32 v87, 0xbfb8aa3b, v71
	v_mul_f32_e32 v88, 0xbfb8aa3b, v72
	v_mul_f32_e32 v89, 0xbfb8aa3b, v73
	v_exp_f32_e32 v86, v86
	v_exp_f32_e32 v87, v87
	v_exp_f32_e32 v88, v88
	v_exp_f32_e32 v89, v89
	s_nop 0
	v_add_f32_e32 v86, 1.0, v86
	v_add_f32_e32 v87, 1.0, v87
	v_add_f32_e32 v88, 1.0, v88
	v_add_f32_e32 v89, 1.0, v89
	v_rcp_f32_e32 v86, v86
	v_rcp_f32_e32 v87, v87
	v_rcp_f32_e32 v88, v88
	v_rcp_f32_e32 v89, v89
	s_nop 0
	v_mul_f32_e32 v86, v70, v86
	v_mul_f32_e32 v87, v71, v87
	v_mul_f32_e32 v88, v72, v88
	v_mul_f32_e32 v89, v73, v89
	ds_write_b32 v47, v86 offset:20
	ds_write_b32 v47, v87 offset:3092
	ds_write_b32 v47, v88 offset:6164
	ds_write_b32 v47, v89 offset:9236
	s_waitcnt vmcnt(8)
	v_mul_f32_e32 v86, 0xbfb8aa3b, v74
	v_mul_f32_e32 v87, 0xbfb8aa3b, v75
	v_mul_f32_e32 v88, 0xbfb8aa3b, v76
	v_mul_f32_e32 v89, 0xbfb8aa3b, v77
	v_exp_f32_e32 v86, v86
	v_exp_f32_e32 v87, v87
	v_exp_f32_e32 v88, v88
	v_exp_f32_e32 v89, v89
	s_nop 0
	v_add_f32_e32 v86, 1.0, v86
	v_add_f32_e32 v87, 1.0, v87
	v_add_f32_e32 v88, 1.0, v88
	v_add_f32_e32 v89, 1.0, v89
	v_rcp_f32_e32 v86, v86
	v_rcp_f32_e32 v87, v87
	v_rcp_f32_e32 v88, v88
	v_rcp_f32_e32 v89, v89
	s_nop 0
	v_mul_f32_e32 v86, v74, v86
	v_mul_f32_e32 v87, v75, v87
	v_mul_f32_e32 v88, v76, v88
	v_mul_f32_e32 v89, v77, v89
	ds_write_b32 v47, v86 offset:24
	ds_write_b32 v47, v87 offset:3096
	ds_write_b32 v47, v88 offset:6168
	ds_write_b32 v47, v89 offset:9240
	s_waitcnt vmcnt(4)
	v_mul_f32_e32 v86, 0xbfb8aa3b, v78
	v_mul_f32_e32 v87, 0xbfb8aa3b, v79
	v_mul_f32_e32 v88, 0xbfb8aa3b, v80
	v_mul_f32_e32 v89, 0xbfb8aa3b, v81
	v_exp_f32_e32 v86, v86
	v_exp_f32_e32 v87, v87
	v_exp_f32_e32 v88, v88
	v_exp_f32_e32 v89, v89
	s_nop 0
	v_add_f32_e32 v86, 1.0, v86
	v_add_f32_e32 v87, 1.0, v87
	v_add_f32_e32 v88, 1.0, v88
	v_add_f32_e32 v89, 1.0, v89
	v_rcp_f32_e32 v86, v86
	v_rcp_f32_e32 v87, v87
	v_rcp_f32_e32 v88, v88
	v_rcp_f32_e32 v89, v89
	s_nop 0
	v_mul_f32_e32 v86, v78, v86
	v_mul_f32_e32 v87, v79, v87
	v_mul_f32_e32 v88, v80, v88
	v_mul_f32_e32 v89, v81, v89
	ds_write_b32 v47, v86 offset:28
	ds_write_b32 v47, v87 offset:3100
	ds_write_b32 v47, v88 offset:6172
	ds_write_b32 v47, v89 offset:9244
	s_waitcnt vmcnt(0)
	v_mul_f32_e32 v86, 0xbfb8aa3b, v82
	v_mul_f32_e32 v87, 0xbfb8aa3b, v83
	v_mul_f32_e32 v88, 0xbfb8aa3b, v84
	v_mul_f32_e32 v89, 0xbfb8aa3b, v85
	v_exp_f32_e32 v86, v86
	v_exp_f32_e32 v87, v87
	v_exp_f32_e32 v88, v88
	v_exp_f32_e32 v89, v89
	s_nop 0
	v_add_f32_e32 v86, 1.0, v86
	v_add_f32_e32 v87, 1.0, v87
	v_add_f32_e32 v88, 1.0, v88
	v_add_f32_e32 v89, 1.0, v89
	v_rcp_f32_e32 v86, v86
	v_rcp_f32_e32 v87, v87
	v_rcp_f32_e32 v88, v88
	v_rcp_f32_e32 v89, v89
	s_nop 0
	v_mul_f32_e32 v86, v82, v86
	v_mul_f32_e32 v87, v83, v87
	v_mul_f32_e32 v88, v84, v88
	v_mul_f32_e32 v89, v85, v89
	ds_write_b32 v47, v86 offset:32
	ds_write_b32 v47, v87 offset:3104
	ds_write_b32 v47, v88 offset:6176
	ds_write_b32 v47, v89 offset:9248
